# lever 4: one static s_setprio 1 for wave half wr=1 (takes the extra entry barrier) at each GEMM phase entry, reset after each seam
# baseline (speedup 1.0000x reference)
; #define SEAM(k) do { if (RUN(k) && hi - lo > 1) xcd_barrier(bar); } while (0)
; __global__ void __launch_bounds__(NT) fwd_megakernel(Params P) {
;     ...
;         if (l + 1 < DEPTH) SEAM(pb + 6);
;     }
;     if (RUN(NPHASE - 1)) { if (RUN(NPHASE - 2)) xcd_barrier(bar); p_ln<true>(Y2, nullptr, P.out, P.ln_ffn_g + (DEPTH - 1) * DM, P.ln_ffn_b + (DEPTH - 1) * DM, (const float*)ST2); }
.LBB0_102:
	s_setprio 0
	v_readlane_b32 s4, v255, 29
	v_readlane_b32 s5, v255, 30
	s_mov_b32 s8, 1
	s_mov_b64 s[6:7], 0
	s_and_b64 vcc, exec, s[4:5]
	s_cbranch_vccnz .LBB0_1207

; #define PG8_STAGE(bufoff, gbase, voff) do { _Pragma("unroll") for (int _i = 0; _i < 2; ++_i) \
;         __builtin_amdgcn_global_load_lds((const unsigned*)((const char*)(gbase) + (voff)[_i]), (PG8_LAS unsigned*)(lds + (bufoff) + ldsw + _i * 8192), 16, 0, 0); } while (0)
; #define PG8_BAR __builtin_amdgcn_s_barrier()
; template <class Epi, class Sched, bool ALIGN_EPI = false, bool SP2 = false>
; __device__ __forceinline__ void gemm_phase(PG8_LAS unsigned char* lds, const Gemm g, const Sched& S, const Epi& E) {
;     int tid_ = mk_tid(); asm volatile("" : "+v"(tid_));
;     const int tid = tid_, wid = __builtin_amdgcn_readfirstlane(tid >> 6), lane = tid & 63, wr = wid >> 2, wc = wid & 3, fr = lane & 15, fq = lane >> 4;
;     const int K = g.K, nt = K / BK;
;     unsigned voffA[2], voffB[2];
; #pragma unroll
;     for (int i = 0; i < 2; ++i) { int R, C; stage_rc(tid * 16 + i * 8192, R, C); const int Rb = Epi::PERM ? ((R & ~31) + perm32(R & 31)) : R;
;         voffA[i] = (unsigned)(R * K + C) * 2u; voffB[i] = (unsigned)(Rb * K + C) * 2u; }
;     const size_t kstep = (size_t)(BK * 2);
;     const size_t hstep = (size_t)HALF * K * 2;
;     const size_t tstep = 2 * hstep;
;     const unsigned ldsw = (unsigned)wid * 1024u;
;     const int aoff = lds_byte(wr * 64 + fr, fq * 8), boff = lds_byte(wc * 32 + fr, fq * 8);
;     ...
;     Unit cur, nxt; int ui = 0;
;     if (!S.next(0, cur)) return;
;     f32x4 acc[2][2][4][2];
; #pragma unroll
;     for (int a = 0; a < 2; ++a)
; #pragma unroll
;         for (int b = 0; b < 2; ++b)
; #pragma unroll
;             for (int m = 0; m < 4; ++m)
; #pragma unroll
;                 for (int n = 0; n < 2; ++n) acc[a][b][m][n] = (f32x4){0.f, 0.f, 0.f, 0.f};
;     bf16x8 At[4][2], B0[2][2], B1[2][2];
;     const char* cA = (const char*)g.A + (size_t)cur.pm * tstep; const char* cB = (const char*)g.Bt + (size_t)cur.pn * tstep;
;     S.a_ready(cur);
;     if constexpr (SP2) {
;         PG8_STAGE(PG8_SB(0, 0), cB, voffB); PG8_STAGE(PG8_SB(0, 1), cB + hstep, voffB); PG8_STAGE(PG8_SA(0, 0), cA, voffA); PG8_STAGE(PG8_SA(0, 1), cA + hstep, voffA);
;         if (wr == 1) PG8_BAR;
.LBB0_176:
	s_waitcnt lgkmcnt(0)
	s_barrier
	s_getreg_b32 s5, hwreg(HW_REG_HW_ID, 0, 6)
	s_and_b32 s5, s5, 63
	s_lshl_b32 s5, s5, 2
	s_or_b32 s5, s5, 0x25000
	v_mov_b32_e32 v1, s5
	ds_read_b32 v1, v1
	v_readlane_b32 s8, v253, 28
	v_mbcnt_lo_u32_b32 v2, -1, 0
	v_mbcnt_hi_u32_b32 v2, -1, v2
	v_readlane_b32 s9, v253, 29
	s_andn2_b64 vcc, exec, s[8:9]
	s_waitcnt lgkmcnt(0)
	v_readfirstlane_b32 s5, v1
	s_waitcnt vmcnt(5)
	s_nop 0
	v_lshl_add_u32 v12, s5, 6, v2
	s_nop 0
	v_readfirstlane_b32 s12, v12
	s_cbranch_vccnz .LBB0_258
	v_lshlrev_b32_e32 v1, 4, v12
	v_add_u32_e32 v2, 0x2000, v1
	v_ashrrev_i32_e32 v3, 31, v2
	v_lshrrev_b32_e32 v3, 22, v3
	v_add_u32_e32 v3, v2, v3
	v_ashrrev_i32_e32 v6, 10, v3
	v_mul_i32_i24_e32 v3, 0x400, v6
	v_sub_u32_e32 v2, v2, v3
	v_lshrrev_b32_e32 v3, 4, v2
	v_bitop3_b32 v2, v3, v2, 32 bitop3:0x6c
	v_ashrrev_i32_e32 v3, 31, v2
	v_lshrrev_b32_e32 v3, 26, v3
	v_add_u32_e32 v3, v2, v3
	v_lshlrev_b32_e32 v4, 3, v6
	v_ashrrev_i32_e32 v7, 6, v3
	v_and_b32_e32 v4, -16, v4
	v_add_u32_e32 v4, v7, v4
	v_and_b32_e32 v5, 3, v7
	s_mov_b32 s8, 0x1fffe0
	v_lshrrev_b32_e32 v8, 2, v4
	v_lshlrev_b32_e32 v9, 1, v4
	v_and_b32_e32 v3, 0xc0, v3
	v_and_or_b32 v5, v4, s8, v5
	v_and_b32_e32 v8, 4, v8
	v_and_b32_e32 v9, 24, v9
	v_sub_u32_e32 v2, v2, v3
	v_or3_b32 v5, v5, v8, v9
	v_lshlrev_b32_e32 v8, 5, v6
	v_ashrrev_i16_sdwa v2, v252, sext(v2) dst_sel:DWORD dst_unused:UNUSED_PAD src0_sel:DWORD src1_sel:BYTE_0
	v_and_b32_e32 v9, 32, v8
	v_bfe_i32 v8, v2, 0, 16
	v_add_lshl_u32 v2, v9, v8, 1
	v_lshl_add_u32 v14, v5, 11, v2
	v_lshl_add_u32 v166, v4, 11, v2
	v_bfe_i32 v2, v12, 27, 1
	v_lshrrev_b32_e32 v2, 22, v2
	v_add_u32_e32 v2, v1, v2
	v_and_b32_e32 v2, 0xfffffc00, v2
	v_sub_u32_e32 v1, v1, v2
	v_lshrrev_b32_e32 v2, 4, v1
	v_ashrrev_i32_e32 v3, 31, v12
	v_bitop3_b32 v1, v2, v1, 32 bitop3:0x6c
	v_lshrrev_b32_e32 v3, 26, v3
	v_ashrrev_i32_e32 v2, 31, v1
	v_add_u32_e32 v3, v12, v3
	v_lshrrev_b32_e32 v2, 26, v2
	v_ashrrev_i32_e32 v10, 6, v3
	v_add_u32_e32 v2, v1, v2
	v_lshlrev_b32_e32 v3, 3, v10
	v_ashrrev_i32_e32 v9, 6, v2
	v_and_b32_e32 v3, -16, v3
	v_add_u32_e32 v3, v9, v3
	v_and_b32_e32 v4, 3, v9
	v_lshrrev_b32_e32 v5, 2, v3
	v_lshlrev_b32_e32 v11, 1, v3
	v_and_b32_e32 v2, 0xc0, v2
	s_ashr_i32 s14, s12, 6
	v_and_or_b32 v4, v3, s8, v4
	v_and_b32_e32 v5, 4, v5
	v_and_b32_e32 v11, 24, v11
	v_sub_u32_e32 v1, v1, v2
	s_ashr_i32 s16, s12, 8
	s_lshl_b32 s5, s14, 10
	v_or3_b32 v4, v4, v5, v11
	v_lshlrev_b32_e32 v5, 5, v10
	v_ashrrev_i16_sdwa v1, v252, sext(v1) dst_sel:DWORD dst_unused:UNUSED_PAD src0_sel:DWORD src1_sel:BYTE_0
	v_readlane_b32 s8, v254, 37
	v_and_b32_e32 v5, 32, v5
	v_bfe_i32 v11, v1, 0, 16
	v_readlane_b32 s9, v254, 38
	s_add_u32 s22, s75, s8
	v_add_lshl_u32 v1, v5, v11, 1
	s_addc_u32 s23, s4, s9
	s_add_i32 s10, s5, 0
	v_lshl_add_u32 v168, v4, 11, v1
	s_add_i32 m0, s10, 0x10000
	v_lshl_add_u32 v170, v3, 11, v1
	global_load_lds_dwordx4 v168, s[22:23]
	s_add_i32 m0, s10, 0x12000
	s_add_u32 s8, s22, 0x40000
	global_load_lds_dwordx4 v14, s[22:23]
	s_addc_u32 s9, s23, 0
	s_add_i32 m0, s10, 0x14000
	s_add_i32 s11, s10, 0x2000
	global_load_lds_dwordx4 v168, s[8:9]
	s_add_i32 m0, s10, 0x16000
	s_add_i32 s26, s10, 0x4000
	global_load_lds_dwordx4 v14, s[8:9]
	v_readlane_b32 s8, v254, 43
	s_mov_b32 m0, s10
	v_readlane_b32 s9, v254, 44
	s_add_i32 s27, s10, 0x6000
	v_mov_b32_e32 v169, v0
	s_waitcnt vmcnt(0)
	v_mov_b32_e32 v15, v0
	s_cmp_eq_u32 s16, 1
	v_lshl_add_u64 v[2:3], s[22:23], 0, v[168:169]
	global_load_lds_dwordx4 v170, s[8:9]
	s_mov_b32 m0, s11
	v_lshl_add_u64 v[4:5], s[22:23], 0, v[14:15]
	global_load_lds_dwordx4 v166, s[8:9]
	v_readlane_b32 s8, v254, 45
	s_mov_b32 m0, s26
	v_readlane_b32 s9, v254, 46
	s_nop 4
	global_load_lds_dwordx4 v170, s[8:9]
	s_mov_b32 m0, s27
	s_nop 0
	global_load_lds_dwordx4 v166, s[8:9]
	s_cselect_b64 s[8:9], -1, 0
	s_cmp_lg_u32 s16, 1
	s_cbranch_scc1 .LBB0_179
	s_setprio 1
	s_barrier

; #define PG8_STAGE(bufoff, gbase, voff) do { _Pragma("unroll") for (int _i = 0; _i < 2; ++_i) \
;         __builtin_amdgcn_global_load_lds((const unsigned*)((const char*)(gbase) + (voff)[_i]), (PG8_LAS unsigned*)(lds + (bufoff) + ldsw + _i * 8192), 16, 0, 0); } while (0)
; #define PG8_BAR __builtin_amdgcn_s_barrier()
; template <class Epi, class Sched, bool ALIGN_EPI = false, bool SP2 = false>
; __device__ __forceinline__ void gemm_phase(PG8_LAS unsigned char* lds, const Gemm g, const Sched& S, const Epi& E) {
;     int tid_ = mk_tid(); asm volatile("" : "+v"(tid_));
;     const int tid = tid_, wid = __builtin_amdgcn_readfirstlane(tid >> 6), lane = tid & 63, wr = wid >> 2, wc = wid & 3, fr = lane & 15, fq = lane >> 4;
;     const int K = g.K, nt = K / BK;
;     unsigned voffA[2], voffB[2];
; #pragma unroll
;     for (int i = 0; i < 2; ++i) { int R, C; stage_rc(tid * 16 + i * 8192, R, C); const int Rb = Epi::PERM ? ((R & ~31) + perm32(R & 31)) : R;
;         voffA[i] = (unsigned)(R * K + C) * 2u; voffB[i] = (unsigned)(Rb * K + C) * 2u; }
;     const size_t kstep = (size_t)(BK * 2);
;     const size_t hstep = (size_t)HALF * K * 2;
;     const size_t tstep = 2 * hstep;
;     const unsigned ldsw = (unsigned)wid * 1024u;
;     const int aoff = lds_byte(wr * 64 + fr, fq * 8), boff = lds_byte(wc * 32 + fr, fq * 8);
;     ...
;     Unit cur, nxt; int ui = 0;
;     if (!S.next(0, cur)) return;
;     f32x4 acc[2][2][4][2];
; #pragma unroll
;     for (int a = 0; a < 2; ++a)
; #pragma unroll
;         for (int b = 0; b < 2; ++b)
; #pragma unroll
;             for (int m = 0; m < 4; ++m)
; #pragma unroll
;                 for (int n = 0; n < 2; ++n) acc[a][b][m][n] = (f32x4){0.f, 0.f, 0.f, 0.f};
;     bf16x8 At[4][2], B0[2][2], B1[2][2];
;     const char* cA = (const char*)g.A + (size_t)cur.pm * tstep; const char* cB = (const char*)g.Bt + (size_t)cur.pn * tstep;
;     S.a_ready(cur);
;     if constexpr (SP2) {
;         PG8_STAGE(PG8_SB(0, 0), cB, voffB); PG8_STAGE(PG8_SB(0, 1), cB + hstep, voffB); PG8_STAGE(PG8_SA(0, 0), cA, voffA); PG8_STAGE(PG8_SA(0, 1), cA + hstep, voffA);
;         if (wr == 1) PG8_BAR;
.LBB0_259:
	s_and_b64 vcc, exec, s[8:9]
	s_cbranch_vccz .LBB0_340
	s_waitcnt lgkmcnt(0)
	v_readfirstlane_b32 s5, v17
	v_readlane_b32 s8, v253, 28
	v_mbcnt_lo_u32_b32 v1, -1, 0
	v_mbcnt_hi_u32_b32 v1, -1, v1
	v_readlane_b32 s9, v253, 29
	v_lshl_add_u32 v2, s5, 6, v1
	s_andn2_b64 vcc, exec, s[8:9]
	v_readfirstlane_b32 s12, v2
	s_cbranch_vccnz .LBB0_340
	v_lshlrev_b32_e32 v1, 4, v2
	v_add_u32_e32 v4, 0x2000, v1
	v_ashrrev_i32_e32 v3, 31, v4
	v_lshrrev_b32_e32 v3, 22, v3
	v_add_u32_e32 v3, v4, v3
	v_ashrrev_i32_e32 v3, 10, v3
	v_mul_i32_i24_e32 v5, 0x400, v3
	v_sub_u32_e32 v4, v4, v5
	v_lshrrev_b32_e32 v5, 4, v4
	v_bitop3_b32 v5, v5, v4, 32 bitop3:0x6c
	v_ashrrev_i32_e32 v4, 31, v5
	v_lshrrev_b32_e32 v4, 26, v4
	v_add_u32_e32 v6, v5, v4
	v_lshlrev_b32_e32 v7, 3, v3
	v_ashrrev_i32_e32 v4, 6, v6
	v_and_b32_e32 v7, -16, v7
	v_add_u32_e32 v7, v4, v7
	v_and_b32_e32 v8, 3, v4
	s_mov_b32 s8, 0x1fffe0
	v_lshrrev_b32_e32 v9, 2, v7
	v_lshlrev_b32_e32 v10, 1, v7
	v_and_b32_e32 v6, 0xc0, v6
	v_and_or_b32 v8, v7, s8, v8
	v_and_b32_e32 v9, 4, v9
	v_and_b32_e32 v10, 24, v10
	v_sub_u32_e32 v5, v5, v6
	v_or3_b32 v8, v8, v9, v10
	v_lshlrev_b32_e32 v9, 5, v3
	v_ashrrev_i16_sdwa v5, v252, sext(v5) dst_sel:DWORD dst_unused:UNUSED_PAD src0_sel:DWORD src1_sel:BYTE_0
	v_and_b32_e32 v9, 32, v9
	v_bfe_i32 v5, v5, 0, 16
	v_add_lshl_u32 v6, v9, v5, 1
	v_lshl_add_u32 v14, v8, 11, v6
	v_lshl_add_u32 v134, v7, 11, v6
	v_bfe_i32 v6, v2, 27, 1
	v_lshrrev_b32_e32 v6, 22, v6
	v_add_u32_e32 v6, v1, v6
	v_and_b32_e32 v6, 0xfffffc00, v6
	v_sub_u32_e32 v1, v1, v6
	v_lshrrev_b32_e32 v6, 4, v1
	v_ashrrev_i32_e32 v7, 31, v2
	v_bitop3_b32 v1, v6, v1, 32 bitop3:0x6c
	v_lshrrev_b32_e32 v7, 26, v7
	v_ashrrev_i32_e32 v6, 31, v1
	v_add_u32_e32 v7, v2, v7
	v_lshrrev_b32_e32 v6, 26, v6
	v_ashrrev_i32_e32 v7, 6, v7
	v_add_u32_e32 v8, v1, v6
	v_lshlrev_b32_e32 v9, 3, v7
	v_ashrrev_i32_e32 v6, 6, v8
	v_and_b32_e32 v9, -16, v9
	v_add_u32_e32 v9, v6, v9
	v_and_b32_e32 v10, 3, v6
	v_lshrrev_b32_e32 v11, 2, v9
	v_lshlrev_b32_e32 v12, 1, v9
	v_and_b32_e32 v8, 0xc0, v8
	s_ashr_i32 s14, s12, 6
	v_and_or_b32 v10, v9, s8, v10
	v_and_b32_e32 v11, 4, v11
	v_and_b32_e32 v12, 24, v12
	v_sub_u32_e32 v1, v1, v8
	s_ashr_i32 s15, s12, 8
	s_lshl_b32 s5, s14, 10
	v_or3_b32 v10, v10, v11, v12
	v_lshlrev_b32_e32 v11, 5, v7
	v_ashrrev_i16_sdwa v1, v252, sext(v1) dst_sel:DWORD dst_unused:UNUSED_PAD src0_sel:DWORD src1_sel:BYTE_0
	v_readlane_b32 s8, v254, 37
	v_and_b32_e32 v11, 32, v11
	v_bfe_i32 v8, v1, 0, 16
	v_readlane_b32 s9, v254, 38
	s_add_u32 s22, s75, s8
	v_add_lshl_u32 v1, v11, v8, 1
	s_addc_u32 s23, s4, s9
	s_add_i32 s10, s5, 0
	v_lshl_add_u32 v136, v10, 11, v1
	s_add_i32 m0, s10, 0x10000
	v_lshl_add_u32 v138, v9, 11, v1
	global_load_lds_dwordx4 v136, s[22:23]
	s_add_i32 m0, s10, 0x12000
	s_add_u32 s8, s22, 0x40000
	global_load_lds_dwordx4 v14, s[22:23]
	s_addc_u32 s9, s23, 0
	s_add_i32 m0, s10, 0x14000
	s_add_i32 s11, s10, 0x2000
	global_load_lds_dwordx4 v136, s[8:9]
	s_add_i32 m0, s10, 0x16000
	s_add_i32 s20, s10, 0x4000
	global_load_lds_dwordx4 v14, s[8:9]
	v_readlane_b32 s8, v254, 49
	s_mov_b32 m0, s10
	v_readlane_b32 s9, v254, 50
	s_add_i32 s26, s10, 0x6000
	s_cmp_eq_u32 s15, 1
	s_nop 2
	global_load_lds_dwordx4 v138, s[8:9]
	s_mov_b32 m0, s11
	s_nop 0
	global_load_lds_dwordx4 v134, s[8:9]
	v_readlane_b32 s8, v254, 51
	s_mov_b32 m0, s20
	v_readlane_b32 s9, v254, 52
	s_nop 4
	global_load_lds_dwordx4 v138, s[8:9]
	s_mov_b32 m0, s26
	s_nop 0
	global_load_lds_dwordx4 v134, s[8:9]
	s_cselect_b64 s[8:9], -1, 0
	s_cmp_lg_u32 s15, 1
	s_cbranch_scc1 .LBB0_263
	s_setprio 1
	s_barrier

; #define LAS __attribute__((address_space(3)))
; __device__ __forceinline__ void p_attn_sb(const Params& P, LAS unsigned char* lds) {
;     ATT_COMMON_SETUP
;     LAS int* flags = (LAS int*)(lds + A_FL);
;     h16x8 uf[2], ones;
; #pragma unroll
;     for (int ks = 0; ks < 2; ++ks)
; #pragma unroll
;         for (int jj = 0; jj < 8; ++jj) { const int k = 16 * ks + 8 * (jj >> 2) + 4 * hh + (jj & 3); uf[ks][jj] = (k > r) ? (h16)1.0f : (h16)0.0f; }
; #pragma unroll
;     for (int jj = 0; jj < 8; ++jj) ones[jj] = (h16)1.0f;
; __global__ void __launch_bounds__(NT) fwd_megakernel(Params P) {
;     ...
;         if (RUN(pb + 2)) { if (l == 0) { p_cs_finalize(P); p_attn_moba(P, lds_raw); } else p_attn_sb(P, lds); }
.LBB0_390:
	s_setprio 0
	v_readlane_b32 s5, v255, 31
	s_or_b32 s5, s5, 3
	s_cmp_gt_i32 s68, s5
	s_cselect_b64 s[6:7], -1, 0
	s_cmp_ge_i32 s5, s69
	s_cselect_b64 s[8:9], -1, 0
	s_or_b64 s[6:7], s[6:7], s[8:9]
	v_writelane_b32 v255, s6, 33
	s_and_b64 vcc, exec, s[6:7]
	s_nop 0
	v_writelane_b32 v255, s7, 34
	s_cbranch_vccnz .LBB0_644
	s_getreg_b32 s5, hwreg(HW_REG_HW_ID, 0, 6)
	s_and_b32 s5, s5, 63
	s_lshl_b32 s5, s5, 2
	s_or_b32 s5, s5, 0x25000
	v_mov_b32_e32 v1, s5
	s_waitcnt vmcnt(0) lgkmcnt(0)
	ds_read_b32 v17, v1
	v_readlane_b32 s8, v255, 29
	v_readlane_b32 s9, v255, 30
	s_mov_b64 s[6:7], -1
	s_and_b64 vcc, exec, s[8:9]
	s_cbranch_vccz .LBB0_411
	v_mbcnt_lo_u32_b32 v1, -1, 0
	v_mbcnt_hi_u32_b32 v1, -1, v1
	s_waitcnt lgkmcnt(0)
	v_readfirstlane_b32 s5, v17
	v_readlane_b32 s6, v254, 20
	v_readlane_b32 s7, v254, 21
	v_lshl_add_u32 v1, s5, 6, v1
	s_andn2_b64 vcc, exec, s[6:7]
	v_readfirstlane_b32 s5, v1
	s_cbranch_vccnz .LBB0_410
	v_bfe_u32 v2, v1, 5, 1
	v_and_b32_e32 v163, 31, v1
	v_lshlrev_b32_e32 v162, 2, v2
	v_cmp_gt_u32_e32 vcc, v162, v163
	v_mov_b32_e32 v12, 0x3c00
	v_or_b32_e32 v6, 17, v162
	v_cndmask_b32_e32 v4, 0, v12, vcc
	v_cmp_lt_u32_e32 vcc, v162, v163
	v_or_b32_e32 v8, 19, v162
	v_or_b32_e32 v7, 24, v162
	v_cndmask_b32_e64 v5, v12, 0, vcc
	v_pack_b32_f16 v98, v4, v5
	v_or_b32_e32 v4, 3, v162
	v_or_b32_e32 v5, 2, v162
	v_cmp_gt_u32_e32 vcc, v4, v163
	v_or_b32_e32 v9, 26, v162
	v_or_b32_e32 v10, 25, v162
	v_cndmask_b32_e32 v4, 0, v12, vcc
	v_cmp_gt_u32_e32 vcc, v5, v163
	v_or_b32_e32 v11, 27, v162
	v_ashrrev_i32_e32 v165, 3, v1
	v_cndmask_b32_e32 v5, 0, v12, vcc
	v_pack_b32_f16 v99, v5, v4
	v_or_b32_e32 v4, 9, v162
	v_or_b32_e32 v5, 8, v162
	v_cmp_gt_u32_e32 vcc, v4, v163
	s_ashr_i32 s5, s5, 6
	s_movk_i32 s6, 0x90
	v_cndmask_b32_e32 v4, 0, v12, vcc
	v_cmp_gt_u32_e32 vcc, v5, v163
	v_and_b32_e32 v3, 63, v1
	v_cmp_gt_i32_e64 s[36:37], 16, v1
	v_cndmask_b32_e32 v5, 0, v12, vcc
	v_pack_b32_f16 v100, v5, v4
	v_or_b32_e32 v4, 11, v162
	v_or_b32_e32 v5, 10, v162
	v_cmp_gt_u32_e32 vcc, v4, v163
	s_lshl_b32 s10, s5, 5
	v_cmp_eq_u32_e64 s[38:39], 0, v3
	v_cndmask_b32_e32 v4, 0, v12, vcc
	v_cmp_gt_u32_e32 vcc, v5, v163
	v_lshlrev_b32_e32 v166, 1, v162
	s_mov_b32 s20, s2
	v_cndmask_b32_e32 v5, 0, v12, vcc
	v_pack_b32_f16 v101, v5, v4
	v_or_b32_e32 v4, 16, v162
	v_cmp_gt_u32_e32 vcc, v4, v163
	v_or_b32_e32 v5, 18, v162
	s_nop 0
	v_cndmask_b32_e32 v4, 0, v12, vcc
	v_cmp_gt_u32_e32 vcc, v6, v163
	s_nop 1
	v_cndmask_b32_e32 v6, 0, v12, vcc
	v_cmp_gt_u32_e32 vcc, v5, v163
	v_pack_b32_f16 v102, v4, v6
	v_lshlrev_b32_e32 v6, 2, v1
	v_cndmask_b32_e32 v5, 0, v12, vcc
	v_cmp_gt_u32_e32 vcc, v8, v163
	v_lshlrev_b32_e32 v4, 4, v2
	v_add_u32_e32 v174, 0, v6
	v_cndmask_b32_e32 v8, 0, v12, vcc
	v_cmp_gt_u32_e32 vcc, v7, v163
	v_pack_b32_f16 v103, v5, v8
	v_lshrrev_b32_e32 v5, 2, v1
	v_cndmask_b32_e32 v7, 0, v12, vcc
	v_cmp_gt_u32_e32 vcc, v9, v163
	v_and_or_b32 v5, v5, 3, v162
	v_and_b32_e32 v8, 7, v1
	v_cndmask_b32_e32 v9, 0, v12, vcc
	v_cmp_gt_u32_e32 vcc, v10, v163
	v_mul_u32_u24_e32 v5, 0x90, v5
	v_lshlrev_b32_e32 v2, 3, v2
	v_cndmask_b32_e32 v10, 0, v12, vcc
	v_cmp_gt_u32_e32 vcc, v11, v163
	v_pack_b32_f16 v104, v7, v10
	v_and_b32_e32 v7, 16, v1
	v_cndmask_b32_e32 v11, 0, v12, vcc
	v_and_or_b32 v7, v6, 12, v7
	v_pack_b32_f16 v105, v9, v11
	v_lshlrev_b32_e32 v7, 1, v7
	v_mul_u32_u24_e32 v9, 0x90, v163
	v_mul_lo_u32 v1, v165, s6
	v_lshlrev_b32_e32 v6, 4, v8
	s_lshl_b32 s6, s5, 2
	v_lshlrev_b32_e32 v164, 3, v8
	v_add3_u32 v175, 0, v1, v6
	v_add3_u32 v176, 0, v9, v4
	v_add3_u32 v177, 0, v5, v7
	s_add_i32 s11, s6, 0
	v_lshlrev_b32_e32 v168, 1, v2
	s_mov_b32 s81, 0
	s_branch .LBB0_395

; #define LAS __attribute__((address_space(3)))
;     __host__ __device__ bool next(int i, Unit& u) const {
;         const long L = (long)i * G + c; if (L >= nwg) return false;
;         int wgid = (int)L; { const int q = nwg / NXCD, r = nwg % NXCD, xcd = wgid % NXCD, off = wgid / NXCD; wgid = (xcd < r ? xcd * (q + 1) : r * (q + 1) + (xcd - r) * q) + off; }
;         const int nig = WGM * nN, gid = wgid / nig, fm = gid * WGM, gsz = (nM - fm) < WGM ? (nM - fm) : WGM;
;         u.pm = fm + ((wgid % nig) % gsz); u.pn = (wgid % nig) / gsz; if (rev) u.pm = nM - 1 - u.pm; return true;
; template <class Sched> __device__ __forceinline__ void p_fill_tables(LAS unsigned char* lds, const float* part, const Sched& S, const float* cvec, const float* bvec) {
;     int tid_ = mk_tid(); asm volatile("" : "+v"(tid_)); const int tid = tid_;
;     LAS unsigned char* tb = lds + ST_OFF; LAS pg8::f32x2_t* st = (LAS pg8::f32x2_t*)tb; LAS float* csl = (LAS float*)(tb + 8192); LAS float* bwl = (LAS float*)(tb + 12288); LAS int* sl = (LAS int*)(tb + 16384);
;     if (tid < 16) { pg8::Unit u; const bool ok = S.next(tid, u); sl[48 + tid] = ok ? u.pm : -1; sl[64 + tid] = ok ? u.pn : -1; }
.LBB0_694:
	s_setprio 0
	v_readlane_b32 s5, v255, 31
	s_or_b32 s5, s5, 4
	s_cmp_gt_i32 s68, s5
	s_cselect_b64 s[6:7], -1, 0
	s_cmp_ge_i32 s5, s69
	s_cselect_b64 s[8:9], -1, 0
	s_or_b64 s[6:7], s[6:7], s[8:9]
	s_and_b64 vcc, exec, s[6:7]
	s_cbranch_vccnz .LBB0_847
	s_add_u32 s5, s75, 0x600000
	s_getreg_b32 s8, hwreg(HW_REG_HW_ID, 0, 6)
	s_addc_u32 s10, s4, 0
	s_and_b32 s8, s8, 63
	s_lshl_b32 s8, s8, 2
	s_or_b32 s8, s8, 0x25000
	v_mov_b32_e32 v1, s8
	s_waitcnt vmcnt(0) lgkmcnt(0)
	ds_read_b32 v17, v1
	v_readlane_b32 s12, v255, 29
	v_readlane_b32 s13, v255, 30
	s_mov_b64 s[8:9], -1
	s_and_b64 vcc, exec, s[12:13]
	s_cbranch_vccz .LBB0_810
	s_waitcnt lgkmcnt(0)
	v_readfirstlane_b32 s8, v17
	v_mbcnt_lo_u32_b32 v1, -1, 0
	v_mbcnt_hi_u32_b32 v1, -1, v1
	s_nop 1
	v_lshl_add_u32 v14, s8, 6, v1
	s_nop 0
	v_cmp_gt_i32_e32 vcc, 16, v14
	s_and_saveexec_b64 s[8:9], vcc
	s_cbranch_execz .LBB0_704
	v_mov_b64_e32 v[2:3], s[2:3]
	v_mad_i64_i32 v[2:3], s[12:13], v14, s70, v[2:3]
	s_mov_b64 s[12:13], 0x400
	s_nop 0
	v_cmp_gt_i64_e64 s[36:37], s[12:13], v[2:3]
	v_mov_b32_e32 v3, -1
	v_mov_b32_e32 v1, -1
	s_and_saveexec_b64 s[14:15], s[36:37]
	s_cbranch_execz .LBB0_703
	v_ashrrev_i32_e32 v1, 31, v2
	v_lshrrev_b32_e32 v1, 29, v1
	v_add_u32_e32 v1, v2, v1
	v_and_b32_e32 v3, -8, v1
	v_sub_u32_e32 v3, v2, v3
	v_cmp_lt_i32_e64 s[36:37], -1, v3
	s_and_saveexec_b64 s[12:13], s[36:37]
	s_xor_b64 s[16:17], exec, s[12:13]
	v_lshlrev_b32_e32 v2, 7, v3
	s_andn2_saveexec_b64 s[16:17], s[16:17]
	v_lshl_add_u32 v2, v3, 7, v3
	s_or_b64 exec, exec, s[16:17]
	v_ashrrev_i32_e32 v1, 3, v1
	v_add_u32_e32 v1, v2, v1
	v_ashrrev_i32_e32 v2, 31, v1
	v_lshrrev_b32_e32 v2, 27, v2
	v_add_u32_e32 v2, v1, v2
	v_ashrrev_i32_e32 v3, 5, v2
	v_lshlrev_b32_e32 v3, 3, v3
	v_sub_u32_e32 v4, 0x100, v3
	v_min_i32_e32 v4, 8, v4
	v_sub_u32_e32 v6, 0, v4
	v_max_i32_e32 v6, v4, v6
	v_cvt_f32_u32_e32 v7, v6
	v_and_b32_e32 v2, 0xffffffe0, v2
	v_sub_u32_e32 v8, 0, v6
	v_sub_u32_e32 v2, v1, v2
	v_rcp_iflag_f32_e32 v7, v7
	v_sub_u32_e32 v5, 0, v2
	v_max_i32_e32 v5, v2, v5
	v_xor_b32_e32 v1, v2, v4
	v_mul_f32_e32 v7, 0x4f7ffffe, v7
	v_cvt_u32_f32_e32 v7, v7
	v_ashrrev_i32_e32 v1, 31, v1
	v_mul_lo_u32 v8, v8, v7
	v_mul_hi_u32 v8, v7, v8
	v_add_u32_e32 v7, v7, v8
	v_mul_hi_u32 v7, v5, v7
	v_mul_lo_u32 v8, v7, v6
	v_sub_u32_e32 v5, v5, v8
	v_cmp_ge_u32_e64 s[36:37], v5, v6
	v_add_u32_e32 v8, 1, v7
	s_nop 0
	v_cndmask_b32_e64 v7, v7, v8, s[36:37]
	v_sub_u32_e32 v8, v5, v6
	v_cndmask_b32_e64 v5, v5, v8, s[36:37]
	v_cmp_ge_u32_e64 s[36:37], v5, v6
	v_add_u32_e32 v5, 1, v7
	s_nop 0
	v_cndmask_b32_e64 v5, v7, v5, s[36:37]
	v_xor_b32_e32 v5, v5, v1
	v_sub_u32_e32 v1, v5, v1
	v_mul_lo_u32 v4, v1, v4
	v_sub_u32_e32 v2, v2, v4
	v_add_u32_e32 v3, v3, v2

; #define PG8_STAGE(bufoff, gbase, voff) do { _Pragma("unroll") for (int _i = 0; _i < 2; ++_i) \
;         __builtin_amdgcn_global_load_lds((const unsigned*)((const char*)(gbase) + (voff)[_i]), (PG8_LAS unsigned*)(lds + (bufoff) + ldsw + _i * 8192), 16, 0, 0); } while (0)
; #define PG8_BAR __builtin_amdgcn_s_barrier()
; template <class Epi, class Sched, bool ALIGN_EPI = false, bool SP2 = false>
; __device__ __forceinline__ void gemm_phase(PG8_LAS unsigned char* lds, const Gemm g, const Sched& S, const Epi& E) {
;     int tid_ = mk_tid(); asm volatile("" : "+v"(tid_));
;     const int tid = tid_, wid = __builtin_amdgcn_readfirstlane(tid >> 6), lane = tid & 63, wr = wid >> 2, wc = wid & 3, fr = lane & 15, fq = lane >> 4;
;     const int K = g.K, nt = K / BK;
;     unsigned voffA[2], voffB[2];
; #pragma unroll
;     for (int i = 0; i < 2; ++i) { int R, C; stage_rc(tid * 16 + i * 8192, R, C); const int Rb = Epi::PERM ? ((R & ~31) + perm32(R & 31)) : R;
;         voffA[i] = (unsigned)(R * K + C) * 2u; voffB[i] = (unsigned)(Rb * K + C) * 2u; }
;     const size_t kstep = (size_t)(BK * 2);
;     const size_t hstep = (size_t)HALF * K * 2;
;     const size_t tstep = 2 * hstep;
;     const unsigned ldsw = (unsigned)wid * 1024u;
;     const int aoff = lds_byte(wr * 64 + fr, fq * 8), boff = lds_byte(wc * 32 + fr, fq * 8);
;     ...
;     Unit cur, nxt; int ui = 0;
;     if (!S.next(0, cur)) return;
;     f32x4 acc[2][2][4][2];
; #pragma unroll
;     for (int a = 0; a < 2; ++a)
; #pragma unroll
;         for (int b = 0; b < 2; ++b)
; #pragma unroll
;             for (int m = 0; m < 4; ++m)
; #pragma unroll
;                 for (int n = 0; n < 2; ++n) acc[a][b][m][n] = (f32x4){0.f, 0.f, 0.f, 0.f};
;     bf16x8 At[4][2], B0[2][2], B1[2][2];
;     const char* cA = (const char*)g.A + (size_t)cur.pm * tstep; const char* cB = (const char*)g.Bt + (size_t)cur.pn * tstep;
;     S.a_ready(cur);
;     if constexpr (SP2) {
;         PG8_STAGE(PG8_SB(0, 0), cB, voffB); PG8_STAGE(PG8_SB(0, 1), cB + hstep, voffB); PG8_STAGE(PG8_SA(0, 0), cA, voffA); PG8_STAGE(PG8_SA(0, 1), cA + hstep, voffA);
;         if (wr == 1) PG8_BAR;
.LBB0_771:
	s_waitcnt lgkmcnt(0)
	s_barrier
	s_getreg_b32 s8, hwreg(HW_REG_HW_ID, 0, 6)
	s_and_b32 s8, s8, 63
	s_lshl_b32 s8, s8, 2
	s_or_b32 s8, s8, 0x25000
	v_mov_b32_e32 v1, s8
	ds_read_b32 v1, v1
	v_mbcnt_lo_u32_b32 v2, -1, 0
	v_mbcnt_hi_u32_b32 v2, -1, v2
	s_waitcnt lgkmcnt(0)
	v_readfirstlane_b32 s8, v1
	s_waitcnt vmcnt(5)
	s_nop 0
	v_lshl_add_u32 v11, s8, 6, v2
	v_readlane_b32 s8, v254, 24
	v_readlane_b32 s9, v254, 25
	s_andn2_b64 vcc, exec, s[8:9]
	v_readfirstlane_b32 s14, v11
	s_cbranch_vccnz .LBB0_809
	v_lshlrev_b32_e32 v2, 4, v11
	v_add_u32_e32 v3, 0x2000, v2
	v_ashrrev_i32_e32 v1, 31, v3
	v_lshrrev_b32_e32 v1, 22, v1
	v_add_u32_e32 v1, v3, v1
	v_ashrrev_i32_e32 v1, 10, v1
	v_mul_i32_i24_e32 v4, 0x400, v1
	v_sub_u32_e32 v3, v3, v4
	v_lshrrev_b32_e32 v4, 4, v3
	v_bitop3_b32 v3, v4, v3, 32 bitop3:0x6c
	v_ashrrev_i32_e32 v4, 31, v3
	v_lshrrev_b32_e32 v4, 26, v4
	v_add_u32_e32 v4, v3, v4
	v_lshlrev_b32_e32 v5, 3, v1
	v_ashrrev_i32_e32 v6, 6, v4
	v_and_b32_e32 v5, -16, v5
	v_add_u32_e32 v5, v6, v5
	v_and_b32_e32 v7, 3, v6
	s_mov_b32 s8, 0x1fffe0
	v_lshrrev_b32_e32 v8, 2, v5
	v_lshlrev_b32_e32 v9, 1, v5
	v_and_b32_e32 v4, 0xc0, v4
	v_and_or_b32 v7, v5, s8, v7
	v_and_b32_e32 v8, 4, v8
	v_and_b32_e32 v9, 24, v9
	v_sub_u32_e32 v3, v3, v4
	v_or3_b32 v8, v7, v8, v9
	v_lshlrev_b32_e32 v7, 5, v1
	v_ashrrev_i16_sdwa v3, v252, sext(v3) dst_sel:DWORD dst_unused:UNUSED_PAD src0_sel:DWORD src1_sel:BYTE_0
	v_and_b32_e32 v9, 32, v7
	v_bfe_i32 v7, v3, 0, 16
	v_add_lshl_u32 v3, v9, v7, 1
	v_lshl_add_u32 v14, v8, 11, v3
	v_lshl_add_u32 v190, v5, 11, v3
	v_bfe_i32 v3, v11, 27, 1
	v_lshrrev_b32_e32 v3, 22, v3
	v_add_u32_e32 v3, v2, v3
	v_and_b32_e32 v3, 0xfffffc00, v3
	v_sub_u32_e32 v2, v2, v3
	v_lshrrev_b32_e32 v3, 4, v2
	v_ashrrev_i32_e32 v4, 31, v11
	v_bitop3_b32 v2, v3, v2, 32 bitop3:0x6c
	v_lshrrev_b32_e32 v4, 26, v4
	v_ashrrev_i32_e32 v3, 31, v2
	v_add_u32_e32 v4, v11, v4
	v_lshrrev_b32_e32 v3, 26, v3
	v_ashrrev_i32_e32 v9, 6, v4
	v_add_u32_e32 v3, v2, v3
	v_lshlrev_b32_e32 v4, 3, v9
	v_ashrrev_i32_e32 v8, 6, v3
	v_and_b32_e32 v4, -16, v4
	v_add_u32_e32 v4, v8, v4
	v_and_b32_e32 v5, 3, v8
	v_lshrrev_b32_e32 v10, 2, v4
	v_lshlrev_b32_e32 v12, 1, v4
	v_and_b32_e32 v3, 0xc0, v3
	s_ashr_i32 s15, s14, 6
	v_and_or_b32 v5, v4, s8, v5
	v_and_b32_e32 v10, 4, v10
	v_and_b32_e32 v12, 24, v12
	v_sub_u32_e32 v2, v2, v3
	s_ashr_i32 s12, s14, 8
	s_lshl_b32 s11, s15, 10
	v_or3_b32 v5, v5, v10, v12
	v_lshlrev_b32_e32 v10, 5, v9
	v_ashrrev_i16_sdwa v2, v252, sext(v2) dst_sel:DWORD dst_unused:UNUSED_PAD src0_sel:DWORD src1_sel:BYTE_0
	v_readlane_b32 s8, v254, 55
	v_and_b32_e32 v12, 32, v10
	v_bfe_i32 v10, v2, 0, 16
	v_readlane_b32 s9, v254, 56
	s_add_u32 s22, s5, s8
	v_add_lshl_u32 v2, v12, v10, 1
	s_addc_u32 s23, s10, s9
	s_add_i32 s28, s11, 0
	v_lshl_add_u32 v192, v5, 11, v2
	s_add_i32 m0, s28, 0x10000
	v_lshl_add_u32 v194, v4, 11, v2
	global_load_lds_dwordx4 v192, s[22:23]
	s_add_i32 m0, s28, 0x12000
	s_add_u32 s8, s22, 0x40000
	global_load_lds_dwordx4 v14, s[22:23]
	s_addc_u32 s9, s23, 0
	s_add_i32 m0, s28, 0x14000
	s_add_i32 s33, s28, 0x2000
	global_load_lds_dwordx4 v192, s[8:9]
	s_add_i32 m0, s28, 0x16000
	s_add_i32 s49, s28, 0x4000
	global_load_lds_dwordx4 v14, s[8:9]
	v_readlane_b32 s8, v254, 59
	s_mov_b32 m0, s28
	v_readlane_b32 s9, v254, 60
	s_add_i32 s71, s28, 0x6000
	v_mov_b32_e32 v193, v0
	s_waitcnt vmcnt(0)
	v_mov_b32_e32 v15, v0
	s_cmp_eq_u32 s12, 1
	v_lshl_add_u64 v[2:3], s[22:23], 0, v[192:193]
	global_load_lds_dwordx4 v194, s[8:9]
	s_mov_b32 m0, s33
	v_lshl_add_u64 v[4:5], s[22:23], 0, v[14:15]
	global_load_lds_dwordx4 v190, s[8:9]
	v_readlane_b32 s8, v254, 61
	s_mov_b32 m0, s49
	v_readlane_b32 s9, v254, 62
	s_nop 4
	global_load_lds_dwordx4 v194, s[8:9]
	s_mov_b32 m0, s71
	s_nop 0
	global_load_lds_dwordx4 v190, s[8:9]
	s_cselect_b64 s[8:9], -1, 0
	s_cmp_lg_u32 s12, 1
	s_cbranch_scc1 .LBB0_774
	s_setprio 1
	s_barrier

; #define PG8_STAGE(bufoff, gbase, voff) do { _Pragma("unroll") for (int _i = 0; _i < 2; ++_i) \
;         __builtin_amdgcn_global_load_lds((const unsigned*)((const char*)(gbase) + (voff)[_i]), (PG8_LAS unsigned*)(lds + (bufoff) + ldsw + _i * 8192), 16, 0, 0); } while (0)
; #define PG8_BAR __builtin_amdgcn_s_barrier()
; template <class Epi, class Sched, bool ALIGN_EPI = false, bool SP2 = false>
; __device__ __forceinline__ void gemm_phase(PG8_LAS unsigned char* lds, const Gemm g, const Sched& S, const Epi& E) {
;     int tid_ = mk_tid(); asm volatile("" : "+v"(tid_));
;     const int tid = tid_, wid = __builtin_amdgcn_readfirstlane(tid >> 6), lane = tid & 63, wr = wid >> 2, wc = wid & 3, fr = lane & 15, fq = lane >> 4;
;     const int K = g.K, nt = K / BK;
;     unsigned voffA[2], voffB[2];
; #pragma unroll
;     for (int i = 0; i < 2; ++i) { int R, C; stage_rc(tid * 16 + i * 8192, R, C); const int Rb = Epi::PERM ? ((R & ~31) + perm32(R & 31)) : R;
;         voffA[i] = (unsigned)(R * K + C) * 2u; voffB[i] = (unsigned)(Rb * K + C) * 2u; }
;     const size_t kstep = (size_t)(BK * 2);
;     const size_t hstep = (size_t)HALF * K * 2;
;     const size_t tstep = 2 * hstep;
;     const unsigned ldsw = (unsigned)wid * 1024u;
;     const int aoff = lds_byte(wr * 64 + fr, fq * 8), boff = lds_byte(wc * 32 + fr, fq * 8);
;     ...
;     Unit cur, nxt; int ui = 0;
;     if (!S.next(0, cur)) return;
;     f32x4 acc[2][2][4][2];
; #pragma unroll
;     for (int a = 0; a < 2; ++a)
; #pragma unroll
;         for (int b = 0; b < 2; ++b)
; #pragma unroll
;             for (int m = 0; m < 4; ++m)
; #pragma unroll
;                 for (int n = 0; n < 2; ++n) acc[a][b][m][n] = (f32x4){0.f, 0.f, 0.f, 0.f};
;     bf16x8 At[4][2], B0[2][2], B1[2][2];
;     const char* cA = (const char*)g.A + (size_t)cur.pm * tstep; const char* cB = (const char*)g.Bt + (size_t)cur.pn * tstep;
;     S.a_ready(cur);
;     if constexpr (SP2) {
;         PG8_STAGE(PG8_SB(0, 0), cB, voffB); PG8_STAGE(PG8_SB(0, 1), cB + hstep, voffB); PG8_STAGE(PG8_SA(0, 0), cA, voffA); PG8_STAGE(PG8_SA(0, 1), cA + hstep, voffA);
;         if (wr == 1) PG8_BAR;
.LBB0_810:
	s_and_b64 vcc, exec, s[8:9]
	s_cbranch_vccz .LBB0_847
	s_waitcnt lgkmcnt(0)
	v_readfirstlane_b32 s8, v17
	v_mbcnt_lo_u32_b32 v1, -1, 0
	v_mbcnt_hi_u32_b32 v1, -1, v1
	s_nop 1
	v_lshl_add_u32 v7, s8, 6, v1
	v_readlane_b32 s8, v254, 24
	v_readlane_b32 s9, v254, 25
	s_andn2_b64 vcc, exec, s[8:9]
	v_readfirstlane_b32 s12, v7
	s_cbranch_vccnz .LBB0_847
	v_lshlrev_b32_e32 v4, 4, v7
	v_add_u32_e32 v2, 0x2000, v4
	v_ashrrev_i32_e32 v1, 31, v2
	v_lshrrev_b32_e32 v1, 22, v1
	v_add_u32_e32 v1, v2, v1
	v_ashrrev_i32_e32 v1, 10, v1
	v_mul_i32_i24_e32 v3, 0x400, v1
	v_sub_u32_e32 v2, v2, v3
	v_lshrrev_b32_e32 v3, 4, v2
	v_bitop3_b32 v3, v3, v2, 32 bitop3:0x6c
	v_ashrrev_i32_e32 v2, 31, v3
	v_lshrrev_b32_e32 v2, 26, v2
	v_add_u32_e32 v5, v3, v2
	v_lshlrev_b32_e32 v6, 3, v1
	v_ashrrev_i32_e32 v2, 6, v5
	v_and_b32_e32 v6, -16, v6
	v_add_u32_e32 v6, v2, v6
	v_and_b32_e32 v8, 3, v2
	s_mov_b32 s8, 0x1fffe0
	v_lshrrev_b32_e32 v9, 2, v6
	v_lshlrev_b32_e32 v10, 1, v6
	v_and_b32_e32 v5, 0xc0, v5
	v_and_or_b32 v8, v6, s8, v8
	v_and_b32_e32 v9, 4, v9
	v_and_b32_e32 v10, 24, v10
	v_sub_u32_e32 v3, v3, v5
	v_or3_b32 v8, v8, v9, v10
	v_lshlrev_b32_e32 v9, 5, v1
	v_ashrrev_i16_sdwa v3, v252, sext(v3) dst_sel:DWORD dst_unused:UNUSED_PAD src0_sel:DWORD src1_sel:BYTE_0
	v_and_b32_e32 v9, 32, v9
	v_bfe_i32 v3, v3, 0, 16
	v_add_lshl_u32 v5, v9, v3, 1
	v_lshl_add_u32 v14, v8, 11, v5
	s_waitcnt vmcnt(0)
	v_lshl_add_u32 v158, v6, 11, v5
	v_bfe_i32 v5, v7, 27, 1
	v_lshrrev_b32_e32 v5, 22, v5
	v_add_u32_e32 v5, v4, v5
	v_and_b32_e32 v5, 0xfffffc00, v5
	v_sub_u32_e32 v4, v4, v5
	v_lshrrev_b32_e32 v5, 4, v4
	v_bitop3_b32 v6, v5, v4, 32 bitop3:0x6c
	v_ashrrev_i32_e32 v5, 31, v7
	v_lshrrev_b32_e32 v5, 26, v5
	v_ashrrev_i32_e32 v4, 31, v6
	v_add_u32_e32 v5, v7, v5
	v_lshrrev_b32_e32 v4, 26, v4
	v_ashrrev_i32_e32 v5, 6, v5
	v_add_u32_e32 v8, v6, v4
	v_lshlrev_b32_e32 v9, 3, v5
	v_ashrrev_i32_e32 v4, 6, v8
	v_and_b32_e32 v9, -16, v9
	v_add_u32_e32 v9, v4, v9
	v_and_b32_e32 v10, 3, v4
	v_lshrrev_b32_e32 v11, 2, v9
	v_lshlrev_b32_e32 v12, 1, v9
	v_and_b32_e32 v8, 0xc0, v8
	s_ashr_i32 s15, s12, 6
	v_and_or_b32 v10, v9, s8, v10
	v_and_b32_e32 v11, 4, v11
	v_and_b32_e32 v12, 24, v12
	v_sub_u32_e32 v6, v6, v8
	s_ashr_i32 s14, s12, 8
	s_lshl_b32 s11, s15, 10
	v_or3_b32 v10, v10, v11, v12
	v_lshlrev_b32_e32 v11, 5, v5
	v_ashrrev_i16_sdwa v6, v252, sext(v6) dst_sel:DWORD dst_unused:UNUSED_PAD src0_sel:DWORD src1_sel:BYTE_0
	v_readlane_b32 s8, v254, 55
	v_and_b32_e32 v11, 32, v11
	v_bfe_i32 v6, v6, 0, 16
	v_readlane_b32 s9, v254, 56
	s_add_u32 s22, s5, s8
	v_add_lshl_u32 v8, v11, v6, 1
	s_addc_u32 s23, s10, s9
	s_add_i32 s28, s11, 0
	v_lshl_add_u32 v160, v10, 11, v8
	s_add_i32 m0, s28, 0x10000
	v_lshl_add_u32 v162, v9, 11, v8
	global_load_lds_dwordx4 v160, s[22:23]
	s_add_i32 m0, s28, 0x12000
	s_add_u32 s8, s22, 0x40000
	global_load_lds_dwordx4 v14, s[22:23]
	s_addc_u32 s9, s23, 0
	s_add_i32 m0, s28, 0x14000
	s_add_i32 s33, s28, 0x2000
	global_load_lds_dwordx4 v160, s[8:9]
	s_add_i32 m0, s28, 0x16000
	s_add_i32 s49, s28, 0x4000
	global_load_lds_dwordx4 v14, s[8:9]
	v_readlane_b32 s8, v254, 59
	s_mov_b32 m0, s28
	v_readlane_b32 s9, v254, 60
	s_add_i32 s71, s28, 0x6000
	s_cmp_eq_u32 s14, 1
	s_nop 2
	global_load_lds_dwordx4 v162, s[8:9]
	s_mov_b32 m0, s33
	s_nop 0
	global_load_lds_dwordx4 v158, s[8:9]
	v_readlane_b32 s8, v254, 61
	s_mov_b32 m0, s49
	v_readlane_b32 s9, v254, 62
	s_nop 4
	global_load_lds_dwordx4 v162, s[8:9]
	s_mov_b32 m0, s71
	s_nop 0
	global_load_lds_dwordx4 v158, s[8:9]
	s_cselect_b64 s[8:9], -1, 0
	s_cmp_lg_u32 s14, 1
	s_cbranch_scc1 .LBB0_814
	s_setprio 1
	s_barrier

; #define LAS __attribute__((address_space(3)))
;     __host__ __device__ bool next(int i, Unit& u) const {
;         const long L = (long)i * G + c; if (L >= nwg) return false;
;         int wgid = (int)L; { const int q = nwg / NXCD, r = nwg % NXCD, xcd = wgid % NXCD, off = wgid / NXCD; wgid = (xcd < r ? xcd * (q + 1) : r * (q + 1) + (xcd - r) * q) + off; }
;         const int nig = WGM * nN, gid = wgid / nig, fm = gid * WGM, gsz = (nM - fm) < WGM ? (nM - fm) : WGM;
;         u.pm = fm + ((wgid % nig) % gsz); u.pn = (wgid % nig) / gsz; if (rev) u.pm = nM - 1 - u.pm; return true;
; template <class Sched> __device__ __forceinline__ void p_fill_tables(LAS unsigned char* lds, const float* part, const Sched& S, const float* cvec, const float* bvec) {
;     int tid_ = mk_tid(); asm volatile("" : "+v"(tid_)); const int tid = tid_;
;     LAS unsigned char* tb = lds + ST_OFF; LAS pg8::f32x2_t* st = (LAS pg8::f32x2_t*)tb; LAS float* csl = (LAS float*)(tb + 8192); LAS float* bwl = (LAS float*)(tb + 12288); LAS int* sl = (LAS int*)(tb + 16384);
;     if (tid < 16) { pg8::Unit u; const bool ok = S.next(tid, u); sl[48 + tid] = ok ? u.pm : -1; sl[64 + tid] = ok ? u.pn : -1; }
.LBB0_897:
	s_setprio 0
	v_readlane_b32 s5, v255, 31
	s_or_b32 s5, s5, 6
	s_cmp_gt_i32 s68, s5
	s_cselect_b64 s[6:7], -1, 0
	s_cmp_ge_i32 s5, s69
	s_cselect_b64 s[8:9], -1, 0
	s_or_b64 s[6:7], s[6:7], s[8:9]
	s_and_b64 vcc, exec, s[6:7]
	s_cbranch_vccnz .LBB0_995
	s_getreg_b32 s5, hwreg(HW_REG_HW_ID, 0, 6)
	s_and_b32 s5, s5, 63
	s_lshl_b32 s5, s5, 2
	s_or_b32 s5, s5, 0x25000
	v_mov_b32_e32 v1, s5
	ds_read_b32 v1, v1
	v_mbcnt_lo_u32_b32 v2, -1, 0
	v_mbcnt_hi_u32_b32 v2, -1, v2
	s_waitcnt lgkmcnt(0)
	v_readfirstlane_b32 s5, v1
	s_nop 1
	v_lshl_add_u32 v14, s5, 6, v2
	s_nop 0
	v_cmp_gt_i32_e32 vcc, 16, v14
	s_and_saveexec_b64 s[8:9], vcc
	s_cbranch_execz .LBB0_906
	v_mov_b64_e32 v[2:3], s[2:3]
	v_mad_i64_i32 v[2:3], s[10:11], v14, s70, v[2:3]
	s_mov_b64 s[10:11], 0x1000
	s_nop 0
	v_cmp_gt_i64_e64 s[36:37], s[10:11], v[2:3]
	v_mov_b32_e32 v3, -1
	v_mov_b32_e32 v1, -1
	s_and_saveexec_b64 s[14:15], s[36:37]
	s_cbranch_execz .LBB0_905
	v_ashrrev_i32_e32 v1, 31, v2
	v_lshrrev_b32_e32 v1, 29, v1
	v_add_u32_e32 v1, v2, v1
	v_and_b32_e32 v3, -8, v1
	v_sub_u32_e32 v3, v2, v3
	v_cmp_lt_i32_e64 s[36:37], -1, v3
	s_and_saveexec_b64 s[10:11], s[36:37]
	s_xor_b64 s[16:17], exec, s[10:11]
	v_lshlrev_b32_e32 v2, 9, v3
	s_andn2_saveexec_b64 s[16:17], s[16:17]
	v_lshl_add_u32 v2, v3, 9, v3
	s_or_b64 exec, exec, s[16:17]
	v_ashrrev_i32_e32 v1, 3, v1
	v_add_u32_e32 v1, v2, v1
	v_ashrrev_i32_e32 v2, 31, v1
	v_lshrrev_b32_e32 v2, 25, v2
	v_add_u32_e32 v2, v1, v2
	v_ashrrev_i32_e32 v3, 7, v2
	v_lshlrev_b32_e32 v3, 3, v3
	v_sub_u32_e32 v4, 0x100, v3
	v_min_i32_e32 v4, 8, v4
	v_sub_u32_e32 v6, 0, v4
	v_max_i32_e32 v6, v4, v6
	v_cvt_f32_u32_e32 v7, v6
	v_and_b32_e32 v2, 0xffffff80, v2
	v_sub_u32_e32 v8, 0, v6
	v_sub_u32_e32 v2, v1, v2
	v_rcp_iflag_f32_e32 v7, v7
	v_sub_u32_e32 v5, 0, v2
	v_max_i32_e32 v5, v2, v5
	v_xor_b32_e32 v1, v2, v4
	v_mul_f32_e32 v7, 0x4f7ffffe, v7
	v_cvt_u32_f32_e32 v7, v7
	v_ashrrev_i32_e32 v1, 31, v1
	v_mul_lo_u32 v8, v8, v7
	v_mul_hi_u32 v8, v7, v8
	v_add_u32_e32 v7, v7, v8
	v_mul_hi_u32 v7, v5, v7
	v_mul_lo_u32 v8, v7, v6
	v_sub_u32_e32 v5, v5, v8
	v_cmp_ge_u32_e64 s[36:37], v5, v6
	v_add_u32_e32 v8, 1, v7
	s_nop 0
	v_cndmask_b32_e64 v7, v7, v8, s[36:37]
	v_sub_u32_e32 v8, v5, v6
	v_cndmask_b32_e64 v5, v5, v8, s[36:37]
	v_cmp_ge_u32_e64 s[36:37], v5, v6
	v_add_u32_e32 v5, 1, v7
	s_nop 0
	v_cndmask_b32_e64 v5, v7, v5, s[36:37]
	v_xor_b32_e32 v5, v5, v1
	v_sub_u32_e32 v1, v5, v1
	v_mul_lo_u32 v4, v1, v4
	v_sub_u32_e32 v2, v2, v4
	v_add_u32_e32 v3, v3, v2

; #define PG8_STAGE(bufoff, gbase, voff) do { _Pragma("unroll") for (int _i = 0; _i < 2; ++_i) \
;         __builtin_amdgcn_global_load_lds((const unsigned*)((const char*)(gbase) + (voff)[_i]), (PG8_LAS unsigned*)(lds + (bufoff) + ldsw + _i * 8192), 16, 0, 0); } while (0)
; #define PG8_BAR __builtin_amdgcn_s_barrier()
; template <class Epi, class Sched, bool ALIGN_EPI = false, bool SP2 = false>
; __device__ __forceinline__ void gemm_phase(PG8_LAS unsigned char* lds, const Gemm g, const Sched& S, const Epi& E) {
;     int tid_ = mk_tid(); asm volatile("" : "+v"(tid_));
;     const int tid = tid_, wid = __builtin_amdgcn_readfirstlane(tid >> 6), lane = tid & 63, wr = wid >> 2, wc = wid & 3, fr = lane & 15, fq = lane >> 4;
;     const int K = g.K, nt = K / BK;
;     unsigned voffA[2], voffB[2];
; #pragma unroll
;     for (int i = 0; i < 2; ++i) { int R, C; stage_rc(tid * 16 + i * 8192, R, C); const int Rb = Epi::PERM ? ((R & ~31) + perm32(R & 31)) : R;
;         voffA[i] = (unsigned)(R * K + C) * 2u; voffB[i] = (unsigned)(Rb * K + C) * 2u; }
;     const size_t kstep = (size_t)(BK * 2);
;     const size_t hstep = (size_t)HALF * K * 2;
;     const size_t tstep = 2 * hstep;
;     const unsigned ldsw = (unsigned)wid * 1024u;
;     const int aoff = lds_byte(wr * 64 + fr, fq * 8), boff = lds_byte(wc * 32 + fr, fq * 8);
;     ...
;     Unit cur, nxt; int ui = 0;
;     if (!S.next(0, cur)) return;
;     f32x4 acc[2][2][4][2];
; #pragma unroll
;     for (int a = 0; a < 2; ++a)
; #pragma unroll
;         for (int b = 0; b < 2; ++b)
; #pragma unroll
;             for (int m = 0; m < 4; ++m)
; #pragma unroll
;                 for (int n = 0; n < 2; ++n) acc[a][b][m][n] = (f32x4){0.f, 0.f, 0.f, 0.f};
;     bf16x8 At[4][2], B0[2][2], B1[2][2];
;     const char* cA = (const char*)g.A + (size_t)cur.pm * tstep; const char* cB = (const char*)g.Bt + (size_t)cur.pn * tstep;
;     S.a_ready(cur);
;     if constexpr (SP2) {
;         PG8_STAGE(PG8_SB(0, 0), cB, voffB); PG8_STAGE(PG8_SB(0, 1), cB + hstep, voffB); PG8_STAGE(PG8_SA(0, 0), cA, voffA); PG8_STAGE(PG8_SA(0, 1), cA + hstep, voffA);
;         if (wr == 1) PG8_BAR;
.LBB0_973:
	s_waitcnt lgkmcnt(0)
	s_barrier
	s_getreg_b32 s5, hwreg(HW_REG_HW_ID, 0, 6)
	s_and_b32 s5, s5, 63
	s_lshl_b32 s5, s5, 2
	s_or_b32 s5, s5, 0x25000
	v_mov_b32_e32 v1, s5
	ds_read_b32 v1, v1
	v_readlane_b32 s8, v254, 20
	v_mbcnt_lo_u32_b32 v2, -1, 0
	v_mbcnt_hi_u32_b32 v2, -1, v2
	v_readlane_b32 s9, v254, 21
	s_andn2_b64 vcc, exec, s[8:9]
	s_waitcnt lgkmcnt(0)
	v_readfirstlane_b32 s5, v1
	s_waitcnt vmcnt(5)
	s_nop 0
	v_lshl_add_u32 v12, s5, 6, v2
	s_nop 0
	v_readfirstlane_b32 s14, v12
	s_cbranch_vccnz .LBB0_995
	v_lshlrev_b32_e32 v1, 4, v12
	v_add_u32_e32 v2, 0x2000, v1
	v_ashrrev_i32_e32 v3, 31, v2
	v_lshrrev_b32_e32 v3, 22, v3
	v_add_u32_e32 v3, v2, v3
	v_ashrrev_i32_e32 v6, 10, v3
	v_mul_i32_i24_e32 v3, 0x400, v6
	v_sub_u32_e32 v2, v2, v3
	v_lshrrev_b32_e32 v3, 4, v2
	v_bitop3_b32 v2, v3, v2, 32 bitop3:0x6c
	v_ashrrev_i32_e32 v3, 31, v2
	v_lshrrev_b32_e32 v3, 26, v3
	v_add_u32_e32 v3, v2, v3
	v_lshlrev_b32_e32 v4, 3, v6
	v_ashrrev_i32_e32 v7, 6, v3
	v_and_b32_e32 v4, -16, v4
	v_add_u32_e32 v4, v7, v4
	v_and_b32_e32 v5, 3, v7
	s_mov_b32 s8, 0x1fffe0
	v_lshrrev_b32_e32 v8, 2, v4
	v_lshlrev_b32_e32 v9, 1, v4
	v_and_b32_e32 v3, 0xc0, v3
	v_and_or_b32 v5, v4, s8, v5
	v_and_b32_e32 v8, 4, v8
	v_and_b32_e32 v9, 24, v9
	v_sub_u32_e32 v2, v2, v3
	v_or3_b32 v5, v5, v8, v9
	v_lshlrev_b32_e32 v8, 5, v6
	v_ashrrev_i16_sdwa v2, v252, sext(v2) dst_sel:DWORD dst_unused:UNUSED_PAD src0_sel:DWORD src1_sel:BYTE_0
	v_and_b32_e32 v9, 32, v8
	v_bfe_i32 v8, v2, 0, 16
	v_add_lshl_u32 v2, v9, v8, 1
	v_lshl_add_u32 v14, v5, 11, v2
	v_lshl_add_u32 v166, v4, 11, v2
	v_bfe_i32 v2, v12, 27, 1
	v_lshrrev_b32_e32 v2, 22, v2
	v_add_u32_e32 v2, v1, v2
	v_and_b32_e32 v2, 0xfffffc00, v2
	v_sub_u32_e32 v1, v1, v2
	v_lshrrev_b32_e32 v2, 4, v1
	v_ashrrev_i32_e32 v3, 31, v12
	v_bitop3_b32 v1, v2, v1, 32 bitop3:0x6c
	v_lshrrev_b32_e32 v3, 26, v3
	v_ashrrev_i32_e32 v2, 31, v1
	v_add_u32_e32 v3, v12, v3
	v_lshrrev_b32_e32 v2, 26, v2
	v_ashrrev_i32_e32 v10, 6, v3
	v_add_u32_e32 v2, v1, v2
	v_lshlrev_b32_e32 v3, 3, v10
	v_ashrrev_i32_e32 v9, 6, v2
	v_and_b32_e32 v3, -16, v3
	s_ashr_i32 s15, s14, 6
	v_add_u32_e32 v3, v9, v3
	s_ashr_i32 s12, s14, 8
	s_lshl_b32 s5, s15, 10
	v_and_b32_e32 v4, 3, v9
	v_lshrrev_b32_e32 v5, 2, v3
	v_lshlrev_b32_e32 v11, 1, v3
	v_and_b32_e32 v2, 0xc0, v2
	s_add_u32 s10, s75, 0x800000
	v_and_or_b32 v4, v3, s8, v4
	v_and_b32_e32 v5, 4, v5
	v_and_b32_e32 v11, 24, v11
	v_sub_u32_e32 v1, v1, v2
	s_addc_u32 s11, s4, 0
	v_or3_b32 v4, v4, v5, v11
	v_lshlrev_b32_e32 v5, 5, v10
	v_ashrrev_i16_sdwa v1, v252, sext(v1) dst_sel:DWORD dst_unused:UNUSED_PAD src0_sel:DWORD src1_sel:BYTE_0
	v_readlane_b32 s8, v254, 27
	v_and_b32_e32 v5, 32, v5
	v_bfe_i32 v11, v1, 0, 16
	v_readlane_b32 s9, v254, 28
	s_add_u32 s22, s10, s8
	v_add_lshl_u32 v1, v5, v11, 1
	s_addc_u32 s23, s11, s9
	s_add_i32 s20, s5, 0
	v_lshl_add_u32 v168, v4, 11, v1
	s_add_i32 m0, s20, 0x10000
	v_lshl_add_u32 v170, v3, 11, v1
	global_load_lds_dwordx4 v168, s[22:23]
	s_add_i32 m0, s20, 0x12000
	s_add_u32 s8, s22, 0x40000
	global_load_lds_dwordx4 v14, s[22:23]
	s_addc_u32 s9, s23, 0
	s_add_i32 m0, s20, 0x14000
	s_add_i32 s26, s20, 0x2000
	global_load_lds_dwordx4 v168, s[8:9]
	s_add_i32 m0, s20, 0x16000
	s_add_i32 s27, s20, 0x4000
	global_load_lds_dwordx4 v14, s[8:9]
	v_readlane_b32 s8, v254, 33
	s_mov_b32 m0, s20
	v_readlane_b32 s9, v254, 34
	s_add_i32 s28, s20, 0x6000
	v_mov_b32_e32 v169, v0
	s_waitcnt vmcnt(0)
	v_mov_b32_e32 v15, v0
	s_cmp_eq_u32 s12, 1
	v_lshl_add_u64 v[2:3], s[22:23], 0, v[168:169]
	global_load_lds_dwordx4 v170, s[8:9]
	s_mov_b32 m0, s26
	v_lshl_add_u64 v[4:5], s[22:23], 0, v[14:15]
	global_load_lds_dwordx4 v166, s[8:9]
	v_readlane_b32 s8, v254, 35
	s_mov_b32 m0, s27
	v_readlane_b32 s9, v254, 36
	s_nop 4
	global_load_lds_dwordx4 v170, s[8:9]
	s_mov_b32 m0, s28
	s_nop 0
	global_load_lds_dwordx4 v166, s[8:9]
	s_cselect_b64 s[8:9], -1, 0
	s_cmp_lg_u32 s12, 1
	s_cbranch_scc1 .LBB0_976
	s_setprio 1
	s_barrier

; #define LAS __attribute__((address_space(3)))
;     __host__ __device__ bool next(int i, Unit& u) const {
;         const long L = (long)i * G + c; if (L >= nwg) return false;
;         int wgid = (int)L; { const int q = nwg / NXCD, r = nwg % NXCD, xcd = wgid % NXCD, off = wgid / NXCD; wgid = (xcd < r ? xcd * (q + 1) : r * (q + 1) + (xcd - r) * q) + off; }
;         const int nig = WGM * nN, gid = wgid / nig, fm = gid * WGM, gsz = (nM - fm) < WGM ? (nM - fm) : WGM;
;         u.pm = fm + ((wgid % nig) % gsz); u.pn = (wgid % nig) / gsz; if (rev) u.pm = nM - 1 - u.pm; return true;
; template <class Sched> __device__ __forceinline__ void p_fill_tables(LAS unsigned char* lds, const float* part, const Sched& S, const float* cvec, const float* bvec) {
;     int tid_ = mk_tid(); asm volatile("" : "+v"(tid_)); const int tid = tid_;
;     LAS unsigned char* tb = lds + ST_OFF; LAS pg8::f32x2_t* st = (LAS pg8::f32x2_t*)tb; LAS float* csl = (LAS float*)(tb + 8192); LAS float* bwl = (LAS float*)(tb + 12288); LAS int* sl = (LAS int*)(tb + 16384);
;     if (tid < 16) { pg8::Unit u; const bool ok = S.next(tid, u); sl[48 + tid] = ok ? u.pm : -1; sl[64 + tid] = ok ? u.pn : -1; }
.LBB0_1045:
	s_setprio 0
	v_readlane_b32 s5, v255, 31
	s_or_b32 s5, s5, 7
	s_cmp_le_i32 s68, s5
	s_cselect_b64 s[6:7], -1, 0
	s_cmp_lt_i32 s5, s69
	s_cselect_b64 s[14:15], -1, 0
	s_and_b64 s[8:9], s[14:15], s[6:7]
	s_andn2_b64 vcc, exec, s[8:9]
	s_cbranch_vccnz .LBB0_1159
	s_getreg_b32 s5, hwreg(HW_REG_HW_ID, 0, 6)
	s_and_b32 s5, s5, 63
	s_lshl_b32 s5, s5, 2
	s_or_b32 s5, s5, 0x25000
	v_mov_b32_e32 v1, s5
	ds_read_b32 v1, v1
	v_mbcnt_lo_u32_b32 v2, -1, 0
	v_mbcnt_hi_u32_b32 v2, -1, v2
	s_waitcnt lgkmcnt(0)
	v_readfirstlane_b32 s5, v1
	s_nop 1
	v_lshl_add_u32 v14, s5, 6, v2
	s_nop 0
	v_cmp_gt_i32_e32 vcc, 16, v14
	s_and_saveexec_b64 s[8:9], vcc
	s_cbranch_execz .LBB0_1054
	v_mov_b64_e32 v[2:3], s[2:3]
	v_mad_i64_i32 v[2:3], s[10:11], v14, s70, v[2:3]
	s_mov_b64 s[10:11], 0x400
	s_nop 0
	v_cmp_gt_i64_e64 s[36:37], s[10:11], v[2:3]
	v_mov_b32_e32 v3, -1
	v_mov_b32_e32 v1, -1
	s_and_saveexec_b64 s[16:17], s[36:37]
	s_cbranch_execz .LBB0_1053
	v_ashrrev_i32_e32 v1, 31, v2
	v_lshrrev_b32_e32 v1, 29, v1
	v_add_u32_e32 v1, v2, v1
	v_and_b32_e32 v3, -8, v1
	v_sub_u32_e32 v3, v2, v3
	v_cmp_lt_i32_e64 s[36:37], -1, v3
	s_and_saveexec_b64 s[10:11], s[36:37]
	s_xor_b64 s[22:23], exec, s[10:11]
	v_lshlrev_b32_e32 v2, 7, v3
	s_andn2_saveexec_b64 s[22:23], s[22:23]
	v_lshl_add_u32 v2, v3, 7, v3
	s_or_b64 exec, exec, s[22:23]
	v_ashrrev_i32_e32 v1, 3, v1
	v_add_u32_e32 v1, v2, v1
	v_ashrrev_i32_e32 v2, 31, v1
	v_lshrrev_b32_e32 v2, 27, v2
	v_add_u32_e32 v2, v1, v2
	v_ashrrev_i32_e32 v3, 5, v2
	v_lshlrev_b32_e32 v3, 3, v3
	v_sub_u32_e32 v4, 0x100, v3
	v_min_i32_e32 v4, 8, v4
	v_sub_u32_e32 v6, 0, v4
	v_max_i32_e32 v6, v4, v6
	v_cvt_f32_u32_e32 v7, v6
	v_and_b32_e32 v2, 0xffffffe0, v2
	v_sub_u32_e32 v8, 0, v6
	v_sub_u32_e32 v2, v1, v2
	v_rcp_iflag_f32_e32 v7, v7
	v_sub_u32_e32 v5, 0, v2
	v_max_i32_e32 v5, v2, v5
	v_xor_b32_e32 v1, v2, v4
	v_mul_f32_e32 v7, 0x4f7ffffe, v7
	v_cvt_u32_f32_e32 v7, v7
	v_ashrrev_i32_e32 v1, 31, v1
	v_mul_lo_u32 v8, v8, v7
	v_mul_hi_u32 v8, v7, v8
	v_add_u32_e32 v7, v7, v8
	v_mul_hi_u32 v7, v5, v7
	v_mul_lo_u32 v8, v7, v6
	v_sub_u32_e32 v5, v5, v8
	v_cmp_ge_u32_e64 s[36:37], v5, v6
	v_add_u32_e32 v8, 1, v7
	s_nop 0
	v_cndmask_b32_e64 v7, v7, v8, s[36:37]
	v_sub_u32_e32 v8, v5, v6
	v_cndmask_b32_e64 v5, v5, v8, s[36:37]
	v_cmp_ge_u32_e64 s[36:37], v5, v6
	v_add_u32_e32 v5, 1, v7
	s_nop 0
	v_cndmask_b32_e64 v5, v7, v5, s[36:37]
	v_xor_b32_e32 v5, v5, v1
	v_sub_u32_e32 v1, v5, v1
	v_mul_lo_u32 v4, v1, v4
	v_sub_u32_e32 v2, v2, v4
	v_add_u32_e32 v2, v2, v3
	v_sub_u32_e32 v3, 0xff, v2

; #define PG8_STAGE(bufoff, gbase, voff) do { _Pragma("unroll") for (int _i = 0; _i < 2; ++_i) \
;         __builtin_amdgcn_global_load_lds((const unsigned*)((const char*)(gbase) + (voff)[_i]), (PG8_LAS unsigned*)(lds + (bufoff) + ldsw + _i * 8192), 16, 0, 0); } while (0)
; #define PG8_BAR __builtin_amdgcn_s_barrier()
; template <class Epi, class Sched, bool ALIGN_EPI = false, bool SP2 = false>
; __device__ __forceinline__ void gemm_phase(PG8_LAS unsigned char* lds, const Gemm g, const Sched& S, const Epi& E) {
;     int tid_ = mk_tid(); asm volatile("" : "+v"(tid_));
;     const int tid = tid_, wid = __builtin_amdgcn_readfirstlane(tid >> 6), lane = tid & 63, wr = wid >> 2, wc = wid & 3, fr = lane & 15, fq = lane >> 4;
;     const int K = g.K, nt = K / BK;
;     unsigned voffA[2], voffB[2];
; #pragma unroll
;     for (int i = 0; i < 2; ++i) { int R, C; stage_rc(tid * 16 + i * 8192, R, C); const int Rb = Epi::PERM ? ((R & ~31) + perm32(R & 31)) : R;
;         voffA[i] = (unsigned)(R * K + C) * 2u; voffB[i] = (unsigned)(Rb * K + C) * 2u; }
;     const size_t kstep = (size_t)(BK * 2);
;     const size_t hstep = (size_t)HALF * K * 2;
;     const size_t tstep = 2 * hstep;
;     const unsigned ldsw = (unsigned)wid * 1024u;
;     const int aoff = lds_byte(wr * 64 + fr, fq * 8), boff = lds_byte(wc * 32 + fr, fq * 8);
;     ...
;     Unit cur, nxt; int ui = 0;
;     if (!S.next(0, cur)) return;
;     f32x4 acc[2][2][4][2];
; #pragma unroll
;     for (int a = 0; a < 2; ++a)
; #pragma unroll
;         for (int b = 0; b < 2; ++b)
; #pragma unroll
;             for (int m = 0; m < 4; ++m)
; #pragma unroll
;                 for (int n = 0; n < 2; ++n) acc[a][b][m][n] = (f32x4){0.f, 0.f, 0.f, 0.f};
;     bf16x8 At[4][2], B0[2][2], B1[2][2];
;     const char* cA = (const char*)g.A + (size_t)cur.pm * tstep; const char* cB = (const char*)g.Bt + (size_t)cur.pn * tstep;
;     S.a_ready(cur);
;     if constexpr (SP2) {
;         PG8_STAGE(PG8_SB(0, 0), cB, voffB); PG8_STAGE(PG8_SB(0, 1), cB + hstep, voffB); PG8_STAGE(PG8_SA(0, 0), cA, voffA); PG8_STAGE(PG8_SA(0, 1), cA + hstep, voffA);
;         if (wr == 1) PG8_BAR;
.LBB0_1121:
	s_waitcnt lgkmcnt(0)
	s_barrier
	s_getreg_b32 s5, hwreg(HW_REG_HW_ID, 0, 6)
	s_and_b32 s5, s5, 63
	s_lshl_b32 s5, s5, 2
	s_or_b32 s5, s5, 0x25000
	v_mov_b32_e32 v1, s5
	ds_read_b32 v1, v1
	v_readlane_b32 s8, v254, 24
	v_mbcnt_lo_u32_b32 v2, -1, 0
	v_mbcnt_hi_u32_b32 v2, -1, v2
	v_readlane_b32 s9, v254, 25
	s_andn2_b64 vcc, exec, s[8:9]
	s_waitcnt lgkmcnt(0)
	v_readfirstlane_b32 s5, v1
	s_waitcnt vmcnt(5)
	s_nop 0
	v_lshl_add_u32 v11, s5, 6, v2
	s_nop 0
	v_readfirstlane_b32 s16, v11
	s_cbranch_vccnz .LBB0_1159
	v_lshlrev_b32_e32 v2, 4, v11
	v_add_u32_e32 v3, 0x2000, v2
	v_ashrrev_i32_e32 v1, 31, v3
	v_lshrrev_b32_e32 v1, 22, v1
	v_add_u32_e32 v1, v3, v1
	v_ashrrev_i32_e32 v1, 10, v1
	v_mul_i32_i24_e32 v4, 0x400, v1
	v_sub_u32_e32 v3, v3, v4
	v_lshrrev_b32_e32 v4, 4, v3
	v_bitop3_b32 v3, v4, v3, 32 bitop3:0x6c
	v_ashrrev_i32_e32 v4, 31, v3
	v_lshrrev_b32_e32 v4, 26, v4
	v_add_u32_e32 v4, v3, v4
	v_lshlrev_b32_e32 v5, 3, v1
	v_ashrrev_i32_e32 v6, 6, v4
	v_and_b32_e32 v5, -16, v5
	v_add_u32_e32 v5, v6, v5
	v_and_b32_e32 v7, 3, v6
	s_mov_b32 s8, 0x7ffe0
	v_lshrrev_b32_e32 v8, 2, v5
	v_lshlrev_b32_e32 v9, 1, v5
	v_and_b32_e32 v4, 0xc0, v4
	v_and_or_b32 v7, v5, s8, v7
	v_and_b32_e32 v8, 4, v8
	v_and_b32_e32 v9, 24, v9
	v_sub_u32_e32 v3, v3, v4
	v_or3_b32 v8, v7, v8, v9
	v_lshlrev_b32_e32 v7, 5, v1
	v_ashrrev_i16_sdwa v3, v252, sext(v3) dst_sel:DWORD dst_unused:UNUSED_PAD src0_sel:DWORD src1_sel:BYTE_0
	v_and_b32_e32 v9, 32, v7
	v_bfe_i32 v7, v3, 0, 16
	v_add_lshl_u32 v3, v9, v7, 1
	v_lshl_add_u32 v14, v8, 13, v3
	v_lshl_add_u32 v190, v5, 13, v3
	v_bfe_i32 v3, v11, 27, 1
	v_lshrrev_b32_e32 v3, 22, v3
	v_add_u32_e32 v3, v2, v3
	v_and_b32_e32 v3, 0xfffffc00, v3
	v_sub_u32_e32 v2, v2, v3
	v_lshrrev_b32_e32 v3, 4, v2
	v_ashrrev_i32_e32 v4, 31, v11
	v_bitop3_b32 v2, v3, v2, 32 bitop3:0x6c
	v_lshrrev_b32_e32 v4, 26, v4
	v_ashrrev_i32_e32 v3, 31, v2
	v_add_u32_e32 v4, v11, v4
	v_lshrrev_b32_e32 v3, 26, v3
	v_ashrrev_i32_e32 v9, 6, v4
	v_add_u32_e32 v3, v2, v3
	v_lshlrev_b32_e32 v4, 3, v9
	v_ashrrev_i32_e32 v8, 6, v3
	v_and_b32_e32 v4, -16, v4
	s_ashr_i32 s17, s16, 6
	v_add_u32_e32 v4, v8, v4
	s_ashr_i32 s12, s16, 8
	s_lshl_b32 s5, s17, 10
	v_and_b32_e32 v5, 3, v8
	v_lshrrev_b32_e32 v10, 2, v4
	v_lshlrev_b32_e32 v12, 1, v4
	v_and_b32_e32 v3, 0xc0, v3
	s_add_u32 s10, s75, 0x1000000
	v_and_or_b32 v5, v4, s8, v5
	v_and_b32_e32 v10, 4, v10
	v_and_b32_e32 v12, 24, v12
	v_sub_u32_e32 v2, v2, v3
	s_addc_u32 s4, s4, 0
	v_or3_b32 v5, v5, v10, v12
	v_lshlrev_b32_e32 v10, 5, v9
	v_ashrrev_i16_sdwa v2, v252, sext(v2) dst_sel:DWORD dst_unused:UNUSED_PAD src0_sel:DWORD src1_sel:BYTE_0
	v_readlane_b32 s8, v254, 63
	v_and_b32_e32 v12, 32, v10
	v_bfe_i32 v10, v2, 0, 16
	v_readlane_b32 s9, v255, 0
	s_add_u32 s22, s10, s8
	v_add_lshl_u32 v2, v12, v10, 1
	s_addc_u32 s23, s4, s9
	s_add_i32 s11, s5, 0
	v_lshl_add_u32 v192, v5, 13, v2
	s_add_i32 m0, s11, 0x10000
	v_lshl_add_u32 v194, v4, 13, v2
	global_load_lds_dwordx4 v192, s[22:23]
	s_add_i32 m0, s11, 0x12000
	s_add_u32 s8, s22, 0x100000
	global_load_lds_dwordx4 v14, s[22:23]
	s_addc_u32 s9, s23, 0
	s_add_i32 m0, s11, 0x14000
	s_add_i32 s28, s11, 0x2000
	global_load_lds_dwordx4 v192, s[8:9]
	s_add_i32 m0, s11, 0x16000
	s_add_i32 s33, s11, 0x4000
	global_load_lds_dwordx4 v14, s[8:9]
	v_readlane_b32 s8, v255, 3
	s_mov_b32 m0, s11
	v_readlane_b32 s9, v255, 4
	s_add_i32 s49, s11, 0x6000
	v_mov_b32_e32 v193, v0
	s_waitcnt vmcnt(0)
	v_mov_b32_e32 v15, v0
	s_cmp_eq_u32 s12, 1
	v_lshl_add_u64 v[2:3], s[22:23], 0, v[192:193]
	global_load_lds_dwordx4 v194, s[8:9]
	s_mov_b32 m0, s28
	v_lshl_add_u64 v[4:5], s[22:23], 0, v[14:15]
	global_load_lds_dwordx4 v190, s[8:9]
	v_readlane_b32 s8, v255, 5
	s_mov_b32 m0, s33
	v_readlane_b32 s9, v255, 6
	s_nop 4
	global_load_lds_dwordx4 v194, s[8:9]
	s_mov_b32 m0, s49
	s_nop 0
	global_load_lds_dwordx4 v190, s[8:9]
	s_cselect_b64 s[8:9], -1, 0
	s_cmp_lg_u32 s12, 1
	s_cbranch_scc1 .LBB0_1124
	s_setprio 1
	s_barrier

; template <bool FINAL> __device__ __forceinline__ void p_ln(const h16* Y, h16* Ho, float* Fo, const float* g, const float* bt, const float* part) {
;     int tid_ = mk_tid(); asm volatile("" : "+v"(tid_)); const int lane = tid_ & 63, w = __builtin_amdgcn_readfirstlane(tid_ >> 6);
;     float gg[16], bb[16];
; #pragma unroll
;     for (int e = 0; e < 8; ++e) { gg[e] = g[8 * lane + e]; gg[8 + e] = g[512 + 8 * lane + e]; bb[e] = bt[8 * lane + e]; bb[8 + e] = bt[512 + 8 * lane + e]; }
;     for (int row = blockIdx.x * 8 + w; row < M_TOK; row += gridDim.x * 8) {
.LBB0_1258:
	s_setprio 0
	s_getreg_b32 s0, hwreg(HW_REG_HW_ID, 0, 6)
	s_and_b32 s0, s0, 63
	s_lshl_b32 s0, s0, 2
	s_or_b32 s0, s0, 0x25000
	v_mov_b32_e32 v0, s0
	ds_read_b32 v0, v0
	v_mbcnt_lo_u32_b32 v1, -1, 0
	v_mbcnt_hi_u32_b32 v1, -1, v1
	s_lshl_b32 s1, s2, 3
	s_waitcnt lgkmcnt(0)
	v_readfirstlane_b32 s0, v0
	s_nop 1
	v_lshl_add_u32 v0, s0, 6, v1
	s_nop 0
	v_readfirstlane_b32 s0, v0
	s_ashr_i32 s0, s0, 6
	s_add_i32 s2, s0, s1
	s_cmp_gt_i32 s2, 0xffff
	s_cbranch_scc1 .LBB0_1261
	s_add_u32 s0, s60, 0x1000
	v_lshlrev_b32_e32 v0, 3, v0
	s_addc_u32 s1, s61, 0
	v_and_b32_e32 v36, 0x1f8, v0
	s_add_u32 s4, s62, 0x1000
	v_lshlrev_b32_e32 v32, 2, v36
	s_addc_u32 s5, s63, 0
	v_or_b32_e32 v33, 0x800, v32
	global_load_dwordx4 v[0:3], v32, s[0:1] offset:16
	global_load_dwordx4 v[4:7], v32, s[0:1]
	global_load_dwordx4 v[8:11], v32, s[4:5] offset:16
	global_load_dwordx4 v[12:15], v32, s[4:5]
	global_load_dwordx4 v[16:19], v33, s[0:1] offset:16
	global_load_dwordx4 v[20:23], v33, s[0:1]
	global_load_dwordx4 v[24:27], v33, s[4:5]
	global_load_dwordx4 v[28:31], v33, s[4:5] offset:16
	v_mov_b32_e32 v33, 0
	v_readlane_b32 s0, v254, 41
	v_lshl_add_u64 v[34:35], s[64:65], 0, v[32:33]
	v_lshlrev_b32_e32 v32, 1, v36
	v_readlane_b32 s1, v254, 42
	s_lshl_b32 s5, s70, 3
	s_mov_b32 s4, 0x3a800000
	v_lshl_add_u64 v[36:37], s[0:1], 0, v[32:33]
	s_mov_b32 s6, 0xf800000
	v_mov_b32_e32 v32, 0x260
